# diff-attn key loops: all 8 K fragments read up front (into the S1 tile + rescale temporaries) before the QK MFMAs; V fragments through a 3-4 deep register ring; next group's sub/exp/cvt spread between
# speedup vs baseline: 1.0421x; 1.0299x over previous
.LBB0_36:
	s_add_i32 s23, s10, -1
	s_and_b32 s23, s23, 1
	s_sub_i32 s26, s22, 63
	s_cmp_gt_u32 s26, s5
	s_cbranch_scc1 .LBB0_43
	s_mul_i32 s26, s23, 0x6900
	s_add_i32 s26, s26, 0
	s_cmp_le_u32 s22, s1
	v_add3_u32 v190, s26, v165, v172
	ds_read_b128 v[98:101], v190
	ds_read_b128 v[102:105], v190 offset:32
	ds_read_b128 v[106:109], v190 offset:64
	ds_read_b128 v[110:113], v190 offset:96
	ds_read_b128 v[240:243], v190 offset:4608
	ds_read_b128 v[244:247], v190 offset:4640
	ds_read_b128 v[214:217], v190 offset:4672
	ds_read_b128 v[190:193], v190 offset:4704
	s_waitcnt lgkmcnt(7)
	v_mfma_f32_32x32x16_bf16 v[82:97], v[98:101], v[126:129], 0
	s_waitcnt lgkmcnt(6)
	v_mfma_f32_32x32x16_bf16 v[82:97], v[102:105], v[130:133], v[82:97]
	s_waitcnt lgkmcnt(5)
	v_mfma_f32_32x32x16_bf16 v[82:97], v[106:109], v[134:137], v[82:97]
	s_waitcnt lgkmcnt(4)
	v_mfma_f32_32x32x16_bf16 v[82:97], v[110:113], v[138:141], v[82:97]
	s_waitcnt lgkmcnt(3)
	v_mfma_f32_32x32x16_bf16 v[98:113], v[240:243], v[126:129], 0
	s_waitcnt lgkmcnt(2)
	v_mfma_f32_32x32x16_bf16 v[98:113], v[244:247], v[130:133], v[98:113]
	s_waitcnt lgkmcnt(1)
	v_mfma_f32_32x32x16_bf16 v[98:113], v[214:217], v[134:137], v[98:113]
	s_waitcnt lgkmcnt(0)
	v_mfma_f32_32x32x16_bf16 v[98:113], v[190:193], v[138:141], v[98:113]
	s_cbranch_scc1 .LBB0_39
	v_add_u32_e32 v190, s22, v173
	v_subrev_u32_e32 v191, 63, v190
	v_cmp_le_i32_e32 vcc, v191, v179
	v_subrev_u32_e32 v192, 61, v190
	v_subrev_u32_e32 v190, 60, v190
	s_nop 5
	v_cndmask_b32_e32 v98, v220, v98, vcc
	v_cmp_lt_i32_e32 vcc, v191, v176
	s_nop 1
	v_cndmask_b32_e32 v83, v220, v83, vcc
	v_cmp_le_i32_e32 vcc, v191, v176
	s_nop 1
	v_cndmask_b32_e32 v82, v220, v82, vcc
	v_cmp_le_i32_e32 vcc, v191, v180
	s_nop 1
	v_cndmask_b32_e32 v99, v220, v99, vcc
	v_cmp_le_i32_e32 vcc, v192, v176
	s_nop 1
	v_cndmask_b32_e32 v84, v220, v84, vcc
	v_cmp_le_i32_e32 vcc, v191, v181
	s_nop 1
	v_cndmask_b32_e32 v100, v220, v100, vcc
	v_cmp_le_i32_e32 vcc, v190, v176
	s_nop 1
	v_cndmask_b32_e32 v85, v220, v85, vcc
	v_cmp_le_i32_e32 vcc, v191, v182
	s_nop 1
	v_cndmask_b32_e32 v101, v220, v101, vcc
	v_cmp_le_i32_e32 vcc, v191, v183
	s_nop 1
	v_cndmask_b32_e32 v86, v220, v86, vcc
	v_cmp_le_i32_e32 vcc, v191, v184
	s_nop 1
	v_cndmask_b32_e32 v102, v220, v102, vcc
	v_cmp_le_i32_e32 vcc, v191, v185
	s_nop 1
	v_cndmask_b32_e32 v87, v220, v87, vcc
	v_cmp_le_i32_e32 vcc, v191, v186
	s_nop 1
	v_cndmask_b32_e32 v103, v220, v103, vcc
	v_cmp_le_i32_e32 vcc, v191, v187
	s_nop 1
	v_cndmask_b32_e32 v88, v220, v88, vcc
	v_cmp_le_i32_e32 vcc, v191, v188
	s_nop 1
	v_cndmask_b32_e32 v104, v220, v104, vcc
	v_cmp_le_i32_e32 vcc, v191, v189
	s_nop 1
	v_cndmask_b32_e32 v89, v220, v89, vcc
	v_cmp_le_i32_e32 vcc, v191, v195
	s_nop 1
	v_cndmask_b32_e32 v105, v220, v105, vcc
	v_cmp_le_i32_e32 vcc, v191, v196
	s_nop 1
	v_cndmask_b32_e32 v90, v220, v90, vcc
	v_cmp_le_i32_e32 vcc, v191, v197
	s_nop 1
	v_cndmask_b32_e32 v106, v220, v106, vcc
	v_cmp_le_i32_e32 vcc, v191, v198
	s_nop 1
	v_cndmask_b32_e32 v91, v220, v91, vcc
	v_cmp_le_i32_e32 vcc, v191, v199
	s_nop 1
	v_cndmask_b32_e32 v107, v220, v107, vcc
	v_cmp_le_i32_e32 vcc, v191, v200
	s_nop 1
	v_cndmask_b32_e32 v92, v220, v92, vcc
	v_cmp_le_i32_e32 vcc, v191, v201
	s_nop 1
	v_cndmask_b32_e32 v108, v220, v108, vcc
	v_cmp_le_i32_e32 vcc, v191, v202
	s_nop 1
	v_cndmask_b32_e32 v93, v220, v93, vcc
	v_cmp_le_i32_e32 vcc, v191, v203
	s_nop 1
	v_cndmask_b32_e32 v109, v220, v109, vcc
	v_cmp_le_i32_e32 vcc, v191, v204
	s_nop 1
	v_cndmask_b32_e32 v94, v220, v94, vcc
	v_cmp_le_i32_e32 vcc, v191, v205
	s_nop 1
	v_cndmask_b32_e32 v110, v220, v110, vcc
	v_cmp_le_i32_e32 vcc, v191, v228
	s_nop 1
	v_cndmask_b32_e32 v95, v220, v95, vcc
	v_cmp_le_i32_e32 vcc, v191, v229
	s_nop 1
	v_cndmask_b32_e32 v111, v220, v111, vcc
	v_cmp_le_i32_e32 vcc, v191, v230
	s_nop 1
	v_cndmask_b32_e32 v96, v220, v96, vcc
	v_cmp_le_i32_e32 vcc, v191, v231
	s_nop 1
	v_cndmask_b32_e32 v112, v220, v112, vcc
	v_cmp_le_i32_e32 vcc, v191, v232
	s_nop 1
	v_cndmask_b32_e32 v97, v220, v97, vcc
	v_cmp_le_i32_e32 vcc, v191, v233
	s_nop 1
	v_cndmask_b32_e32 v113, v220, v113, vcc

.LBB0_45:
	v_add3_u32 v190, s26, v178, v177
	s_mov_b32 s78, s76
	s_mov_b32 s79, s76
	s_mov_b32 s77, s76
	ds_read_b64_tr_b16 v[240:241], v190 offset:9216
	ds_read_b64_tr_b16 v[242:243], v190 offset:11392
	ds_read_b64_tr_b16 v[244:245], v190 offset:9280
	ds_read_b64_tr_b16 v[246:247], v190 offset:11456
	ds_read_b64_tr_b16 v[214:215], v190 offset:9344
	ds_read_b64_tr_b16 v[216:217], v190 offset:11520
	v_sub_f32_e32 v82, v82, v238
	v_sub_f32_e32 v83, v83, v238
	v_sub_f32_e32 v84, v84, v238
	v_sub_f32_e32 v85, v85, v238
	v_sub_f32_e32 v86, v86, v238
	v_sub_f32_e32 v87, v87, v238
	v_sub_f32_e32 v88, v88, v238
	v_sub_f32_e32 v89, v89, v238
	v_exp_f32_e32 v82, v82
	v_exp_f32_e32 v83, v83
	v_exp_f32_e32 v84, v84
	v_exp_f32_e32 v85, v85
	v_exp_f32_e32 v86, v86
	v_exp_f32_e32 v87, v87
	v_exp_f32_e32 v88, v88
	v_exp_f32_e32 v89, v89
	v_cvt_pk_bf16_f32 v82, v82, v83
	v_cvt_pk_bf16_f32 v83, v84, v85
	v_cvt_pk_bf16_f32 v84, v86, v87
	v_cvt_pk_bf16_f32 v85, v88, v89
	v_mov_b64_e32 v[88:89], s[78:79]
	v_mov_b64_e32 v[86:87], s[76:77]
	s_waitcnt lgkmcnt(4)
	v_mfma_f32_32x32x16_bf16 v[2:17], v[82:85], v[240:243], v[2:17]
	v_sub_f32_e32 v90, v90, v238
	v_sub_f32_e32 v91, v91, v238
	v_sub_f32_e32 v92, v92, v238
	v_sub_f32_e32 v93, v93, v238
	ds_read_b64_tr_b16 v[240:241], v190 offset:9408
	ds_read_b64_tr_b16 v[242:243], v190 offset:11584
	s_waitcnt lgkmcnt(4)
	v_mfma_f32_32x32x16_bf16 v[50:65], v[82:85], v[244:247], v[50:65]
	v_sub_f32_e32 v94, v94, v238
	v_sub_f32_e32 v95, v95, v238
	v_sub_f32_e32 v96, v96, v238
	v_sub_f32_e32 v97, v97, v238
	ds_read_b64_tr_b16 v[244:245], v190 offset:13568
	ds_read_b64_tr_b16 v[246:247], v190 offset:15744
	s_waitcnt lgkmcnt(4)
	v_mfma_f32_32x32x16_bf16 v[34:49], v[82:85], v[214:217], v[34:49]
	v_exp_f32_e32 v90, v90
	v_exp_f32_e32 v91, v91
	v_exp_f32_e32 v92, v92
	v_exp_f32_e32 v93, v93
	ds_read_b64_tr_b16 v[214:215], v190 offset:13632
	ds_read_b64_tr_b16 v[216:217], v190 offset:15808
	s_waitcnt lgkmcnt(4)
	v_mfma_f32_32x32x16_bf16 v[18:33], v[82:85], v[240:243], v[18:33]
	v_exp_f32_e32 v94, v94
	v_exp_f32_e32 v95, v95
	v_exp_f32_e32 v96, v96
	v_exp_f32_e32 v97, v97
	ds_read_b64_tr_b16 v[240:241], v190 offset:13696
	ds_read_b64_tr_b16 v[242:243], v190 offset:15872
	v_mfma_f32_32x32x16_bf16 v[66:81], v[82:85], v[86:89], v[66:81]
	v_cvt_pk_bf16_f32 v90, v90, v91
	v_cvt_pk_bf16_f32 v91, v92, v93
	v_cvt_pk_bf16_f32 v92, v94, v95
	v_cvt_pk_bf16_f32 v93, v96, v97
	s_nop 0
	s_waitcnt lgkmcnt(4)
	v_mfma_f32_32x32x16_bf16 v[2:17], v[90:93], v[244:247], v[2:17]
	v_sub_f32_e32 v98, v98, v238
	v_sub_f32_e32 v99, v99, v238
	v_sub_f32_e32 v100, v100, v238
	v_sub_f32_e32 v101, v101, v238
	ds_read_b64_tr_b16 v[244:245], v190 offset:13760
	ds_read_b64_tr_b16 v[246:247], v190 offset:15936
	s_waitcnt lgkmcnt(4)
	v_mfma_f32_32x32x16_bf16 v[50:65], v[90:93], v[214:217], v[50:65]
	v_sub_f32_e32 v102, v102, v238
	v_sub_f32_e32 v103, v103, v238
	v_sub_f32_e32 v104, v104, v238
	v_sub_f32_e32 v105, v105, v238
	ds_read_b64_tr_b16 v[214:215], v190 offset:17920
	ds_read_b64_tr_b16 v[216:217], v190 offset:20096
	s_waitcnt lgkmcnt(4)
	v_mfma_f32_32x32x16_bf16 v[34:49], v[90:93], v[240:243], v[34:49]
	v_exp_f32_e32 v98, v98
	v_exp_f32_e32 v99, v99
	v_exp_f32_e32 v100, v100
	v_exp_f32_e32 v101, v101
	ds_read_b64_tr_b16 v[240:241], v190 offset:17984
	ds_read_b64_tr_b16 v[242:243], v190 offset:20160
	s_waitcnt lgkmcnt(4)
	v_mfma_f32_32x32x16_bf16 v[18:33], v[90:93], v[244:247], v[18:33]
	v_exp_f32_e32 v102, v102
	v_exp_f32_e32 v103, v103
	v_exp_f32_e32 v104, v104
	v_exp_f32_e32 v105, v105
	ds_read_b64_tr_b16 v[244:245], v190 offset:18048
	ds_read_b64_tr_b16 v[246:247], v190 offset:20224
	v_mfma_f32_32x32x16_bf16 v[66:81], v[90:93], v[86:89], v[66:81]
	v_cvt_pk_bf16_f32 v98, v98, v99
	v_cvt_pk_bf16_f32 v99, v100, v101
	v_cvt_pk_bf16_f32 v100, v102, v103
	v_cvt_pk_bf16_f32 v101, v104, v105
	s_nop 0
	s_waitcnt lgkmcnt(4)
	v_mfma_f32_32x32x16_bf16 v[2:17], v[98:101], v[214:217], v[2:17]
	v_sub_f32_e32 v106, v106, v238
	v_sub_f32_e32 v107, v107, v238
	v_sub_f32_e32 v108, v108, v238
	v_sub_f32_e32 v109, v109, v238
	ds_read_b64_tr_b16 v[214:215], v190 offset:18112
	ds_read_b64_tr_b16 v[216:217], v190 offset:20288
	s_waitcnt lgkmcnt(4)
	v_mfma_f32_32x32x16_bf16 v[50:65], v[98:101], v[240:243], v[50:65]
	v_sub_f32_e32 v110, v110, v238
	v_sub_f32_e32 v111, v111, v238
	v_sub_f32_e32 v112, v112, v238
	v_sub_f32_e32 v113, v113, v238
	ds_read_b64_tr_b16 v[240:241], v190 offset:22272
	ds_read_b64_tr_b16 v[242:243], v190 offset:24448
	s_waitcnt lgkmcnt(4)
	v_mfma_f32_32x32x16_bf16 v[34:49], v[98:101], v[244:247], v[34:49]
	v_exp_f32_e32 v106, v106
	v_exp_f32_e32 v107, v107
	v_exp_f32_e32 v108, v108
	v_exp_f32_e32 v109, v109
	ds_read_b64_tr_b16 v[244:245], v190 offset:22336
	ds_read_b64_tr_b16 v[246:247], v190 offset:24512
	s_waitcnt lgkmcnt(4)
	v_mfma_f32_32x32x16_bf16 v[18:33], v[98:101], v[214:217], v[18:33]
	v_exp_f32_e32 v110, v110
	v_exp_f32_e32 v111, v111
	v_exp_f32_e32 v112, v112
	v_exp_f32_e32 v113, v113
	ds_read_b64_tr_b16 v[214:215], v190 offset:22400
	ds_read_b64_tr_b16 v[216:217], v190 offset:24576
	v_mfma_f32_32x32x16_bf16 v[66:81], v[98:101], v[86:89], v[66:81]
	v_cvt_pk_bf16_f32 v106, v106, v107
	v_cvt_pk_bf16_f32 v107, v108, v109
	v_cvt_pk_bf16_f32 v108, v110, v111
	v_cvt_pk_bf16_f32 v109, v112, v113
	s_nop 0
	s_waitcnt lgkmcnt(4)
	v_mfma_f32_32x32x16_bf16 v[2:17], v[106:109], v[240:243], v[2:17]
	ds_read_b64_tr_b16 v[240:241], v190 offset:22464
	ds_read_b64_tr_b16 v[242:243], v190 offset:24640
	s_waitcnt lgkmcnt(4)
	v_mfma_f32_32x32x16_bf16 v[50:65], v[106:109], v[244:247], v[50:65]
	s_waitcnt lgkmcnt(2)
	v_mfma_f32_32x32x16_bf16 v[34:49], v[106:109], v[214:217], v[34:49]
	s_waitcnt lgkmcnt(0)
	v_mfma_f32_32x32x16_bf16 v[18:33], v[106:109], v[240:243], v[18:33]
	v_mfma_f32_32x32x16_bf16 v[66:81], v[106:109], v[86:89], v[66:81]
	s_movk_i32 s77, 0x110
	s_andn2_b64 vcc, exec, s[60:61]
	s_cbranch_vccnz .LBB0_47

.LBB0_51:
	s_add_i32 s23, s22, -1
	s_and_b32 s23, s23, 1
	s_sub_i32 s26, s10, 63
	s_cmp_gt_u32 s26, s5
	s_cbranch_scc1 .LBB0_58
	s_mul_i32 s26, s23, 0x6900
	s_add_i32 s26, s26, 0
	s_cmp_le_u32 s10, s1
	v_add3_u32 v152, s26, v165, v172
	ds_read_b128 v[98:101], v152
	ds_read_b128 v[102:105], v152 offset:32
	ds_read_b128 v[106:109], v152 offset:64
	ds_read_b128 v[110:113], v152 offset:96
	ds_read_b128 v[154:157], v152 offset:4608
	ds_read_b128 v[190:193], v152 offset:4640
	ds_read_b128 v[214:217], v152 offset:4672
	ds_read_b128 v[234:237], v152 offset:4704
	s_waitcnt lgkmcnt(7)
	v_mfma_f32_32x32x16_bf16 v[82:97], v[98:101], v[114:117], 0
	s_waitcnt lgkmcnt(6)
	v_mfma_f32_32x32x16_bf16 v[82:97], v[102:105], v[118:121], v[82:97]
	s_waitcnt lgkmcnt(5)
	v_mfma_f32_32x32x16_bf16 v[82:97], v[106:109], v[126:129], v[82:97]
	s_waitcnt lgkmcnt(4)
	v_mfma_f32_32x32x16_bf16 v[82:97], v[110:113], v[130:133], v[82:97]
	s_waitcnt lgkmcnt(3)
	v_mfma_f32_32x32x16_bf16 v[98:113], v[154:157], v[114:117], 0
	s_waitcnt lgkmcnt(2)
	v_mfma_f32_32x32x16_bf16 v[98:113], v[190:193], v[118:121], v[98:113]
	s_waitcnt lgkmcnt(1)
	v_mfma_f32_32x32x16_bf16 v[98:113], v[214:217], v[126:129], v[98:113]
	s_waitcnt lgkmcnt(0)
	v_mfma_f32_32x32x16_bf16 v[98:113], v[234:237], v[130:133], v[98:113]
	s_cbranch_scc1 .LBB0_54
	v_add_u32_e32 v152, s10, v173
	v_subrev_u32_e32 v154, 63, v152
	v_cmp_le_i32_e32 vcc, v154, v179
	v_subrev_u32_e32 v155, 61, v152
	v_subrev_u32_e32 v152, 60, v152
	s_nop 5
	v_cndmask_b32_e32 v98, v220, v98, vcc
	v_cmp_lt_i32_e32 vcc, v154, v176
	s_nop 1
	v_cndmask_b32_e32 v83, v220, v83, vcc
	v_cmp_le_i32_e32 vcc, v154, v176
	s_nop 1
	v_cndmask_b32_e32 v82, v220, v82, vcc
	v_cmp_le_i32_e32 vcc, v154, v180
	s_nop 1
	v_cndmask_b32_e32 v99, v220, v99, vcc
	v_cmp_le_i32_e32 vcc, v155, v176
	s_nop 1
	v_cndmask_b32_e32 v84, v220, v84, vcc
	v_cmp_le_i32_e32 vcc, v154, v181
	s_nop 1
	v_cndmask_b32_e32 v100, v220, v100, vcc
	v_cmp_le_i32_e32 vcc, v152, v176
	s_nop 1
	v_cndmask_b32_e32 v85, v220, v85, vcc
	v_cmp_le_i32_e32 vcc, v154, v182
	s_nop 1
	v_cndmask_b32_e32 v101, v220, v101, vcc
	v_cmp_le_i32_e32 vcc, v154, v183
	s_nop 1
	v_cndmask_b32_e32 v86, v220, v86, vcc
	v_cmp_le_i32_e32 vcc, v154, v184
	s_nop 1
	v_cndmask_b32_e32 v102, v220, v102, vcc
	v_cmp_le_i32_e32 vcc, v154, v185
	s_nop 1
	v_cndmask_b32_e32 v87, v220, v87, vcc
	v_cmp_le_i32_e32 vcc, v154, v186
	s_nop 1
	v_cndmask_b32_e32 v103, v220, v103, vcc
	v_cmp_le_i32_e32 vcc, v154, v187
	s_nop 1
	v_cndmask_b32_e32 v88, v220, v88, vcc
	v_cmp_le_i32_e32 vcc, v154, v188
	s_nop 1
	v_cndmask_b32_e32 v104, v220, v104, vcc
	v_cmp_le_i32_e32 vcc, v154, v189
	s_nop 1
	v_cndmask_b32_e32 v89, v220, v89, vcc
	v_cmp_le_i32_e32 vcc, v154, v195
	s_nop 1
	v_cndmask_b32_e32 v105, v220, v105, vcc
	v_cmp_le_i32_e32 vcc, v154, v196
	s_nop 1
	v_cndmask_b32_e32 v90, v220, v90, vcc
	v_cmp_le_i32_e32 vcc, v154, v197
	s_nop 1
	v_cndmask_b32_e32 v106, v220, v106, vcc
	v_cmp_le_i32_e32 vcc, v154, v198
	s_nop 1
	v_cndmask_b32_e32 v91, v220, v91, vcc
	v_cmp_le_i32_e32 vcc, v154, v199
	s_nop 1
	v_cndmask_b32_e32 v107, v220, v107, vcc
	v_cmp_le_i32_e32 vcc, v154, v200
	s_nop 1
	v_cndmask_b32_e32 v92, v220, v92, vcc
	v_cmp_le_i32_e32 vcc, v154, v201
	s_nop 1
	v_cndmask_b32_e32 v108, v220, v108, vcc
	v_cmp_le_i32_e32 vcc, v154, v202
	s_nop 1
	v_cndmask_b32_e32 v93, v220, v93, vcc
	v_cmp_le_i32_e32 vcc, v154, v203
	s_nop 1
	v_cndmask_b32_e32 v109, v220, v109, vcc
	v_cmp_le_i32_e32 vcc, v154, v204
	s_nop 1
	v_cndmask_b32_e32 v94, v220, v94, vcc
	v_cmp_le_i32_e32 vcc, v154, v205
	s_nop 1
	v_cndmask_b32_e32 v110, v220, v110, vcc
	v_cmp_le_i32_e32 vcc, v154, v228
	s_nop 1
	v_cndmask_b32_e32 v95, v220, v95, vcc
	v_cmp_le_i32_e32 vcc, v154, v229
	s_nop 1
	v_cndmask_b32_e32 v111, v220, v111, vcc
	v_cmp_le_i32_e32 vcc, v154, v230
	s_nop 1
	v_cndmask_b32_e32 v96, v220, v96, vcc
	v_cmp_le_i32_e32 vcc, v154, v231
	s_nop 1
	v_cndmask_b32_e32 v112, v220, v112, vcc
	v_cmp_le_i32_e32 vcc, v154, v232
	s_nop 1
	v_cndmask_b32_e32 v97, v220, v97, vcc
	v_cmp_le_i32_e32 vcc, v154, v233
	s_nop 1
	v_cndmask_b32_e32 v113, v220, v113, vcc

.LBB0_60:
	v_add3_u32 v153, s26, v178, v177
	s_mov_b32 s78, s76
	s_mov_b32 s79, s76
	s_mov_b32 s77, s76
	ds_read_b64_tr_b16 v[154:155], v153 offset:9216
	ds_read_b64_tr_b16 v[156:157], v153 offset:11392
	ds_read_b64_tr_b16 v[190:191], v153 offset:9280
	ds_read_b64_tr_b16 v[192:193], v153 offset:11456
	ds_read_b64_tr_b16 v[214:215], v153 offset:9344
	ds_read_b64_tr_b16 v[216:217], v153 offset:11520
	ds_read_b64_tr_b16 v[234:235], v153 offset:9408
	ds_read_b64_tr_b16 v[236:237], v153 offset:11584
	v_sub_f32_e32 v82, v82, v152
	v_sub_f32_e32 v83, v83, v152
	v_sub_f32_e32 v84, v84, v152
	v_sub_f32_e32 v85, v85, v152
	v_sub_f32_e32 v86, v86, v152
	v_sub_f32_e32 v87, v87, v152
	v_sub_f32_e32 v88, v88, v152
	v_sub_f32_e32 v89, v89, v152
	v_exp_f32_e32 v82, v82
	v_exp_f32_e32 v83, v83
	v_exp_f32_e32 v84, v84
	v_exp_f32_e32 v85, v85
	v_exp_f32_e32 v86, v86
	v_exp_f32_e32 v87, v87
	v_exp_f32_e32 v88, v88
	v_exp_f32_e32 v89, v89
	v_cvt_pk_bf16_f32 v82, v82, v83
	v_cvt_pk_bf16_f32 v83, v84, v85
	v_cvt_pk_bf16_f32 v84, v86, v87
	v_cvt_pk_bf16_f32 v85, v88, v89
	v_mov_b64_e32 v[88:89], s[78:79]
	v_mov_b64_e32 v[86:87], s[76:77]
	s_waitcnt lgkmcnt(6)
	v_mfma_f32_32x32x16_bf16 v[2:17], v[82:85], v[154:157], v[2:17]
	v_sub_f32_e32 v90, v90, v152
	v_sub_f32_e32 v91, v91, v152
	v_sub_f32_e32 v92, v92, v152
	v_sub_f32_e32 v93, v93, v152
	ds_read_b64_tr_b16 v[154:155], v153 offset:13568
	ds_read_b64_tr_b16 v[156:157], v153 offset:15744
	s_waitcnt lgkmcnt(6)
	v_mfma_f32_32x32x16_bf16 v[50:65], v[82:85], v[190:193], v[50:65]
	v_sub_f32_e32 v94, v94, v152
	v_sub_f32_e32 v95, v95, v152
	v_sub_f32_e32 v96, v96, v152
	v_sub_f32_e32 v97, v97, v152
	ds_read_b64_tr_b16 v[190:191], v153 offset:13632
	ds_read_b64_tr_b16 v[192:193], v153 offset:15808
	s_waitcnt lgkmcnt(6)
	v_mfma_f32_32x32x16_bf16 v[18:33], v[82:85], v[214:217], v[18:33]
	v_exp_f32_e32 v90, v90
	v_exp_f32_e32 v91, v91
	v_exp_f32_e32 v92, v92
	v_exp_f32_e32 v93, v93
	ds_read_b64_tr_b16 v[214:215], v153 offset:13696
	ds_read_b64_tr_b16 v[216:217], v153 offset:15872
	s_waitcnt lgkmcnt(6)
	v_mfma_f32_32x32x16_bf16 v[34:49], v[82:85], v[234:237], v[34:49]
	v_exp_f32_e32 v94, v94
	v_exp_f32_e32 v95, v95
	v_exp_f32_e32 v96, v96
	v_exp_f32_e32 v97, v97
	ds_read_b64_tr_b16 v[234:235], v153 offset:13760
	ds_read_b64_tr_b16 v[236:237], v153 offset:15936
	v_mfma_f32_32x32x16_bf16 v[66:81], v[82:85], v[86:89], v[66:81]
	v_cvt_pk_bf16_f32 v90, v90, v91
	v_cvt_pk_bf16_f32 v91, v92, v93
	v_cvt_pk_bf16_f32 v92, v94, v95
	v_cvt_pk_bf16_f32 v93, v96, v97
	s_nop 0
	s_waitcnt lgkmcnt(6)
	v_mfma_f32_32x32x16_bf16 v[2:17], v[90:93], v[154:157], v[2:17]
	v_sub_f32_e32 v98, v98, v152
	v_sub_f32_e32 v99, v99, v152
	v_sub_f32_e32 v100, v100, v152
	v_sub_f32_e32 v101, v101, v152
	ds_read_b64_tr_b16 v[154:155], v153 offset:17920
	ds_read_b64_tr_b16 v[156:157], v153 offset:20096
	s_waitcnt lgkmcnt(6)
	v_mfma_f32_32x32x16_bf16 v[50:65], v[90:93], v[190:193], v[50:65]
	v_sub_f32_e32 v102, v102, v152
	v_sub_f32_e32 v103, v103, v152
	v_sub_f32_e32 v104, v104, v152
	v_sub_f32_e32 v105, v105, v152
	ds_read_b64_tr_b16 v[190:191], v153 offset:17984
	ds_read_b64_tr_b16 v[192:193], v153 offset:20160
	s_waitcnt lgkmcnt(6)
	v_mfma_f32_32x32x16_bf16 v[18:33], v[90:93], v[214:217], v[18:33]
	v_exp_f32_e32 v98, v98
	v_exp_f32_e32 v99, v99
	v_exp_f32_e32 v100, v100
	v_exp_f32_e32 v101, v101
	ds_read_b64_tr_b16 v[214:215], v153 offset:18048
	ds_read_b64_tr_b16 v[216:217], v153 offset:20224
	s_waitcnt lgkmcnt(6)
	v_mfma_f32_32x32x16_bf16 v[34:49], v[90:93], v[234:237], v[34:49]
	v_exp_f32_e32 v102, v102
	v_exp_f32_e32 v103, v103
	v_exp_f32_e32 v104, v104
	v_exp_f32_e32 v105, v105
	ds_read_b64_tr_b16 v[234:235], v153 offset:18112
	ds_read_b64_tr_b16 v[236:237], v153 offset:20288
	v_mfma_f32_32x32x16_bf16 v[66:81], v[90:93], v[86:89], v[66:81]
	v_cvt_pk_bf16_f32 v98, v98, v99
	v_cvt_pk_bf16_f32 v99, v100, v101
	v_cvt_pk_bf16_f32 v100, v102, v103
	v_cvt_pk_bf16_f32 v101, v104, v105
	s_nop 0
	s_waitcnt lgkmcnt(6)
	v_mfma_f32_32x32x16_bf16 v[2:17], v[98:101], v[154:157], v[2:17]
	v_sub_f32_e32 v106, v106, v152
	v_sub_f32_e32 v107, v107, v152
	v_sub_f32_e32 v108, v108, v152
	v_sub_f32_e32 v109, v109, v152
	ds_read_b64_tr_b16 v[154:155], v153 offset:22272
	ds_read_b64_tr_b16 v[156:157], v153 offset:24448
	s_waitcnt lgkmcnt(6)
	v_mfma_f32_32x32x16_bf16 v[50:65], v[98:101], v[190:193], v[50:65]
	v_sub_f32_e32 v110, v110, v152
	v_sub_f32_e32 v111, v111, v152
	v_sub_f32_e32 v112, v112, v152
	v_sub_f32_e32 v113, v113, v152
	ds_read_b64_tr_b16 v[190:191], v153 offset:22336
	ds_read_b64_tr_b16 v[192:193], v153 offset:24512
	s_waitcnt lgkmcnt(6)
	v_mfma_f32_32x32x16_bf16 v[18:33], v[98:101], v[214:217], v[18:33]
	v_exp_f32_e32 v106, v106
	v_exp_f32_e32 v107, v107
	v_exp_f32_e32 v108, v108
	v_exp_f32_e32 v109, v109
	ds_read_b64_tr_b16 v[214:215], v153 offset:22400
	ds_read_b64_tr_b16 v[216:217], v153 offset:24576
	s_waitcnt lgkmcnt(6)
	v_mfma_f32_32x32x16_bf16 v[34:49], v[98:101], v[234:237], v[34:49]
	v_exp_f32_e32 v110, v110
	v_exp_f32_e32 v111, v111
	v_exp_f32_e32 v112, v112
	v_exp_f32_e32 v113, v113
	ds_read_b64_tr_b16 v[234:235], v153 offset:22464
	ds_read_b64_tr_b16 v[236:237], v153 offset:24640
	v_mfma_f32_32x32x16_bf16 v[66:81], v[98:101], v[86:89], v[66:81]
	v_cvt_pk_bf16_f32 v106, v106, v107
	v_cvt_pk_bf16_f32 v107, v108, v109
	v_cvt_pk_bf16_f32 v108, v110, v111
	v_cvt_pk_bf16_f32 v109, v112, v113
	s_nop 0
	s_waitcnt lgkmcnt(6)
	v_mfma_f32_32x32x16_bf16 v[2:17], v[106:109], v[154:157], v[2:17]
	s_waitcnt lgkmcnt(4)
	v_mfma_f32_32x32x16_bf16 v[50:65], v[106:109], v[190:193], v[50:65]
	s_waitcnt lgkmcnt(2)
	v_mfma_f32_32x32x16_bf16 v[18:33], v[106:109], v[214:217], v[18:33]
	s_waitcnt lgkmcnt(0)
	v_mfma_f32_32x32x16_bf16 v[34:49], v[106:109], v[234:237], v[34:49]
	v_mfma_f32_32x32x16_bf16 v[66:81], v[106:109], v[86:89], v[66:81]
	s_movk_i32 s77, 0x110
	s_andn2_b64 vcc, exec, s[62:63]
	s_cbranch_vccnz .LBB0_62

.LBB0_66:
	s_add_i32 s23, s4, -1
	s_and_b32 s23, s23, 1
	s_cmp_gt_u32 s22, s11
	s_cbranch_scc1 .LBB0_73
	s_mul_i32 s26, s23, 0x6900
	s_add_i32 s26, s26, 0
	s_add_i32 s30, s22, 63
	s_cmp_le_u32 s30, s1
	v_add3_u32 v206, s26, v177, v178
	ds_read_b128 v[98:101], v206
	ds_read_b128 v[102:105], v206 offset:32
	ds_read_b128 v[106:109], v206 offset:64
	ds_read_b128 v[110:113], v206 offset:96
	ds_read_b128 v[190:193], v206 offset:4608
	ds_read_b128 v[214:217], v206 offset:4640
	ds_read_b128 v[244:247], v206 offset:4672
	ds_read_b128 v[206:209], v206 offset:4704
	s_waitcnt lgkmcnt(7)
	v_mfma_f32_32x32x16_bf16 v[82:97], v[98:101], v[126:129], 0
	s_waitcnt lgkmcnt(6)
	v_mfma_f32_32x32x16_bf16 v[82:97], v[102:105], v[130:133], v[82:97]
	s_waitcnt lgkmcnt(5)
	v_mfma_f32_32x32x16_bf16 v[82:97], v[106:109], v[134:137], v[82:97]
	s_waitcnt lgkmcnt(4)
	v_mfma_f32_32x32x16_bf16 v[82:97], v[110:113], v[138:141], v[82:97]
	s_waitcnt lgkmcnt(3)
	v_mfma_f32_32x32x16_bf16 v[98:113], v[190:193], v[126:129], 0
	s_waitcnt lgkmcnt(2)
	v_mfma_f32_32x32x16_bf16 v[98:113], v[214:217], v[130:133], v[98:113]
	s_waitcnt lgkmcnt(1)
	v_mfma_f32_32x32x16_bf16 v[98:113], v[244:247], v[134:137], v[98:113]
	s_waitcnt lgkmcnt(0)
	v_mfma_f32_32x32x16_bf16 v[98:113], v[206:209], v[138:141], v[98:113]
	s_cbranch_scc1 .LBB0_69
	v_add_u32_e32 v190, s22, v179
	v_cmp_le_i32_e32 vcc, v190, v183
	v_add_u32_e32 v191, 2, v190
	s_nop 7
	v_cndmask_b32_e32 v98, v220, v98, vcc
	v_cmp_lt_i32_e32 vcc, v190, v173
	s_nop 1
	v_cndmask_b32_e32 v83, v220, v83, vcc
	v_cmp_le_i32_e32 vcc, v190, v173
	s_nop 1
	v_cndmask_b32_e32 v82, v220, v82, vcc
	v_cmp_le_i32_e32 vcc, v190, v184
	s_nop 1
	v_cndmask_b32_e32 v99, v220, v99, vcc
	v_cmp_le_i32_e32 vcc, v191, v173
	v_add_u32_e32 v191, 3, v190
	s_nop 0
	v_cndmask_b32_e32 v84, v220, v84, vcc
	v_cmp_le_i32_e32 vcc, v190, v185
	s_nop 1
	v_cndmask_b32_e32 v100, v220, v100, vcc
	v_cmp_le_i32_e32 vcc, v191, v173
	s_nop 1
	v_cndmask_b32_e32 v85, v220, v85, vcc
	v_cmp_le_i32_e32 vcc, v190, v186
	s_nop 1
	v_cndmask_b32_e32 v101, v220, v101, vcc
	v_cmp_le_i32_e32 vcc, v190, v187
	s_nop 1
	v_cndmask_b32_e32 v86, v220, v86, vcc
	v_cmp_le_i32_e32 vcc, v190, v188
	s_nop 1
	v_cndmask_b32_e32 v102, v220, v102, vcc
	v_cmp_le_i32_e32 vcc, v190, v189
	s_nop 1
	v_cndmask_b32_e32 v87, v220, v87, vcc
	v_cmp_le_i32_e32 vcc, v190, v195
	s_nop 1
	v_cndmask_b32_e32 v103, v220, v103, vcc
	v_cmp_le_i32_e32 vcc, v190, v196
	s_nop 1
	v_cndmask_b32_e32 v88, v220, v88, vcc
	v_cmp_le_i32_e32 vcc, v190, v197
	s_nop 1
	v_cndmask_b32_e32 v104, v220, v104, vcc
	v_cmp_le_i32_e32 vcc, v190, v198
	s_nop 1
	v_cndmask_b32_e32 v89, v220, v89, vcc
	v_cmp_le_i32_e32 vcc, v190, v199
	s_nop 1
	v_cndmask_b32_e32 v105, v220, v105, vcc
	v_cmp_le_i32_e32 vcc, v190, v200
	s_nop 1
	v_cndmask_b32_e32 v90, v220, v90, vcc
	v_cmp_le_i32_e32 vcc, v190, v201
	s_nop 1
	v_cndmask_b32_e32 v106, v220, v106, vcc
	v_cmp_le_i32_e32 vcc, v190, v202
	s_nop 1
	v_cndmask_b32_e32 v91, v220, v91, vcc
	v_cmp_le_i32_e32 vcc, v190, v203
	s_nop 1
	v_cndmask_b32_e32 v107, v220, v107, vcc
	v_cmp_le_i32_e32 vcc, v190, v204
	s_nop 1
	v_cndmask_b32_e32 v92, v220, v92, vcc
	v_cmp_le_i32_e32 vcc, v190, v205
	s_nop 1
	v_cndmask_b32_e32 v108, v220, v108, vcc
	v_cmp_le_i32_e32 vcc, v190, v228
	s_nop 1
	v_cndmask_b32_e32 v93, v220, v93, vcc
	v_cmp_le_i32_e32 vcc, v190, v229
	s_nop 1
	v_cndmask_b32_e32 v109, v220, v109, vcc
	v_cmp_le_i32_e32 vcc, v190, v230
	s_nop 1
	v_cndmask_b32_e32 v94, v220, v94, vcc
	v_cmp_le_i32_e32 vcc, v190, v231
	s_nop 1
	v_cndmask_b32_e32 v110, v220, v110, vcc
	v_cmp_le_i32_e32 vcc, v190, v232
	s_nop 1
	v_cndmask_b32_e32 v95, v220, v95, vcc
	v_cmp_le_i32_e32 vcc, v190, v233
	s_nop 1
	v_cndmask_b32_e32 v111, v220, v111, vcc
	v_cmp_le_i32_e32 vcc, v190, v234
	s_nop 1
	v_cndmask_b32_e32 v96, v220, v96, vcc
	v_cmp_le_i32_e32 vcc, v190, v235
	s_nop 1
	v_cndmask_b32_e32 v112, v220, v112, vcc
	v_cmp_le_i32_e32 vcc, v190, v236
	s_nop 1
	v_cndmask_b32_e32 v97, v220, v97, vcc
	v_cmp_le_i32_e32 vcc, v190, v237
	s_nop 1
	v_cndmask_b32_e32 v113, v220, v113, vcc

.LBB0_75:
	v_add3_u32 v190, s26, v182, v181
	s_mov_b32 s78, s76
	s_mov_b32 s79, s76
	s_mov_b32 s77, s76
	ds_read_b64_tr_b16 v[214:215], v190 offset:9216
	ds_read_b64_tr_b16 v[216:217], v190 offset:11392
	ds_read_b64_tr_b16 v[244:245], v190 offset:9280
	ds_read_b64_tr_b16 v[246:247], v190 offset:11456
	ds_read_b64_tr_b16 v[206:207], v190 offset:9344
	ds_read_b64_tr_b16 v[208:209], v190 offset:11520
	v_sub_f32_e32 v82, v82, v242
	v_sub_f32_e32 v83, v83, v242
	v_sub_f32_e32 v84, v84, v242
	v_sub_f32_e32 v85, v85, v242
	v_sub_f32_e32 v86, v86, v242
	v_sub_f32_e32 v87, v87, v242
	v_sub_f32_e32 v88, v88, v242
	v_sub_f32_e32 v89, v89, v242
	v_exp_f32_e32 v82, v82
	v_exp_f32_e32 v83, v83
	v_exp_f32_e32 v84, v84
	v_exp_f32_e32 v85, v85
	v_exp_f32_e32 v86, v86
	v_exp_f32_e32 v87, v87
	v_exp_f32_e32 v88, v88
	v_exp_f32_e32 v89, v89
	v_cvt_pk_bf16_f32 v82, v82, v83
	v_cvt_pk_bf16_f32 v83, v84, v85
	v_cvt_pk_bf16_f32 v84, v86, v87
	v_cvt_pk_bf16_f32 v85, v88, v89
	v_mov_b64_e32 v[88:89], s[78:79]
	v_mov_b64_e32 v[86:87], s[76:77]
	s_waitcnt lgkmcnt(4)
	v_mfma_f32_32x32x16_bf16 v[2:17], v[82:85], v[214:217], v[2:17]
	v_sub_f32_e32 v90, v90, v242
	v_sub_f32_e32 v91, v91, v242
	v_sub_f32_e32 v92, v92, v242
	v_sub_f32_e32 v93, v93, v242
	ds_read_b64_tr_b16 v[214:215], v190 offset:9408
	ds_read_b64_tr_b16 v[216:217], v190 offset:11584
	s_waitcnt lgkmcnt(4)
	v_mfma_f32_32x32x16_bf16 v[50:65], v[82:85], v[244:247], v[50:65]
	v_sub_f32_e32 v94, v94, v242
	v_sub_f32_e32 v95, v95, v242
	v_sub_f32_e32 v96, v96, v242
	v_sub_f32_e32 v97, v97, v242
	ds_read_b64_tr_b16 v[244:245], v190 offset:13568
	ds_read_b64_tr_b16 v[246:247], v190 offset:15744
	s_waitcnt lgkmcnt(4)
	v_mfma_f32_32x32x16_bf16 v[34:49], v[82:85], v[206:209], v[34:49]
	v_exp_f32_e32 v90, v90
	v_exp_f32_e32 v91, v91
	v_exp_f32_e32 v92, v92
	v_exp_f32_e32 v93, v93
	ds_read_b64_tr_b16 v[206:207], v190 offset:13632
	ds_read_b64_tr_b16 v[208:209], v190 offset:15808
	s_waitcnt lgkmcnt(4)
	v_mfma_f32_32x32x16_bf16 v[18:33], v[82:85], v[214:217], v[18:33]
	v_exp_f32_e32 v94, v94
	v_exp_f32_e32 v95, v95
	v_exp_f32_e32 v96, v96
	v_exp_f32_e32 v97, v97
	ds_read_b64_tr_b16 v[214:215], v190 offset:13696
	ds_read_b64_tr_b16 v[216:217], v190 offset:15872
	v_mfma_f32_32x32x16_bf16 v[66:81], v[82:85], v[86:89], v[66:81]
	v_cvt_pk_bf16_f32 v90, v90, v91
	v_cvt_pk_bf16_f32 v91, v92, v93
	v_cvt_pk_bf16_f32 v92, v94, v95
	v_cvt_pk_bf16_f32 v93, v96, v97
	s_nop 0
	s_waitcnt lgkmcnt(4)
	v_mfma_f32_32x32x16_bf16 v[2:17], v[90:93], v[244:247], v[2:17]
	v_sub_f32_e32 v98, v98, v242
	v_sub_f32_e32 v99, v99, v242
	v_sub_f32_e32 v100, v100, v242
	v_sub_f32_e32 v101, v101, v242
	ds_read_b64_tr_b16 v[244:245], v190 offset:13760
	ds_read_b64_tr_b16 v[246:247], v190 offset:15936
	s_waitcnt lgkmcnt(4)
	v_mfma_f32_32x32x16_bf16 v[50:65], v[90:93], v[206:209], v[50:65]
	v_sub_f32_e32 v102, v102, v242
	v_sub_f32_e32 v103, v103, v242
	v_sub_f32_e32 v104, v104, v242
	v_sub_f32_e32 v105, v105, v242
	ds_read_b64_tr_b16 v[206:207], v190 offset:17920
	ds_read_b64_tr_b16 v[208:209], v190 offset:20096
	s_waitcnt lgkmcnt(4)
	v_mfma_f32_32x32x16_bf16 v[34:49], v[90:93], v[214:217], v[34:49]
	v_exp_f32_e32 v98, v98
	v_exp_f32_e32 v99, v99
	v_exp_f32_e32 v100, v100
	v_exp_f32_e32 v101, v101
	ds_read_b64_tr_b16 v[214:215], v190 offset:17984
	ds_read_b64_tr_b16 v[216:217], v190 offset:20160
	s_waitcnt lgkmcnt(4)
	v_mfma_f32_32x32x16_bf16 v[18:33], v[90:93], v[244:247], v[18:33]
	v_exp_f32_e32 v102, v102
	v_exp_f32_e32 v103, v103
	v_exp_f32_e32 v104, v104
	v_exp_f32_e32 v105, v105
	ds_read_b64_tr_b16 v[244:245], v190 offset:18048
	ds_read_b64_tr_b16 v[246:247], v190 offset:20224
	v_mfma_f32_32x32x16_bf16 v[66:81], v[90:93], v[86:89], v[66:81]
	v_cvt_pk_bf16_f32 v98, v98, v99
	v_cvt_pk_bf16_f32 v99, v100, v101
	v_cvt_pk_bf16_f32 v100, v102, v103
	v_cvt_pk_bf16_f32 v101, v104, v105
	s_nop 0
	s_waitcnt lgkmcnt(4)
	v_mfma_f32_32x32x16_bf16 v[2:17], v[98:101], v[206:209], v[2:17]
	v_sub_f32_e32 v106, v106, v242
	v_sub_f32_e32 v107, v107, v242
	v_sub_f32_e32 v108, v108, v242
	v_sub_f32_e32 v109, v109, v242
	ds_read_b64_tr_b16 v[206:207], v190 offset:18112
	ds_read_b64_tr_b16 v[208:209], v190 offset:20288
	s_waitcnt lgkmcnt(4)
	v_mfma_f32_32x32x16_bf16 v[50:65], v[98:101], v[214:217], v[50:65]
	v_sub_f32_e32 v110, v110, v242
	v_sub_f32_e32 v111, v111, v242
	v_sub_f32_e32 v112, v112, v242
	v_sub_f32_e32 v113, v113, v242
	ds_read_b64_tr_b16 v[214:215], v190 offset:22272
	ds_read_b64_tr_b16 v[216:217], v190 offset:24448
	s_waitcnt lgkmcnt(4)
	v_mfma_f32_32x32x16_bf16 v[34:49], v[98:101], v[244:247], v[34:49]
	v_exp_f32_e32 v106, v106
	v_exp_f32_e32 v107, v107
	v_exp_f32_e32 v108, v108
	v_exp_f32_e32 v109, v109
	ds_read_b64_tr_b16 v[244:245], v190 offset:22336
	ds_read_b64_tr_b16 v[246:247], v190 offset:24512
	s_waitcnt lgkmcnt(4)
	v_mfma_f32_32x32x16_bf16 v[18:33], v[98:101], v[206:209], v[18:33]
	v_exp_f32_e32 v110, v110
	v_exp_f32_e32 v111, v111
	v_exp_f32_e32 v112, v112
	v_exp_f32_e32 v113, v113
	ds_read_b64_tr_b16 v[206:207], v190 offset:22400
	ds_read_b64_tr_b16 v[208:209], v190 offset:24576
	v_mfma_f32_32x32x16_bf16 v[66:81], v[98:101], v[86:89], v[66:81]
	v_cvt_pk_bf16_f32 v106, v106, v107
	v_cvt_pk_bf16_f32 v107, v108, v109
	v_cvt_pk_bf16_f32 v108, v110, v111
	v_cvt_pk_bf16_f32 v109, v112, v113
	s_nop 0
	s_waitcnt lgkmcnt(4)
	v_mfma_f32_32x32x16_bf16 v[2:17], v[106:109], v[214:217], v[2:17]
	ds_read_b64_tr_b16 v[214:215], v190 offset:22464
	ds_read_b64_tr_b16 v[216:217], v190 offset:24640
	s_waitcnt lgkmcnt(4)
	v_mfma_f32_32x32x16_bf16 v[50:65], v[106:109], v[244:247], v[50:65]
	s_waitcnt lgkmcnt(2)
	v_mfma_f32_32x32x16_bf16 v[34:49], v[106:109], v[206:209], v[34:49]
	s_waitcnt lgkmcnt(0)
	v_mfma_f32_32x32x16_bf16 v[18:33], v[106:109], v[214:217], v[18:33]
	v_mfma_f32_32x32x16_bf16 v[66:81], v[106:109], v[86:89], v[66:81]
	s_movk_i32 s77, 0x110
	s_andn2_b64 vcc, exec, s[28:29]
	s_cbranch_vccnz .LBB0_77

.LBB0_81:
	s_add_i32 s23, s22, -1
	s_and_b32 s23, s23, 1
	s_cmp_gt_u32 s4, s11
	s_cbranch_scc1 .LBB0_88
	s_mul_i32 s26, s23, 0x6900
	s_add_i32 s26, s26, 0
	s_add_i32 s30, s4, 63
	s_cmp_le_u32 s30, s1
	v_add3_u32 v152, s26, v177, v178
	ds_read_b128 v[98:101], v152
	ds_read_b128 v[102:105], v152 offset:32
	ds_read_b128 v[106:109], v152 offset:64
	ds_read_b128 v[110:113], v152 offset:96
	ds_read_b128 v[154:157], v152 offset:4608
	ds_read_b128 v[162:165], v152 offset:4640
	ds_read_b128 v[190:193], v152 offset:4672
	ds_read_b128 v[206:209], v152 offset:4704
	s_waitcnt lgkmcnt(7)
	v_mfma_f32_32x32x16_bf16 v[82:97], v[98:101], v[118:121], 0
	s_waitcnt lgkmcnt(6)
	v_mfma_f32_32x32x16_bf16 v[82:97], v[102:105], v[122:125], v[82:97]
	s_waitcnt lgkmcnt(5)
	v_mfma_f32_32x32x16_bf16 v[82:97], v[106:109], v[126:129], v[82:97]
	s_waitcnt lgkmcnt(4)
	v_mfma_f32_32x32x16_bf16 v[82:97], v[110:113], v[134:137], v[82:97]
	s_waitcnt lgkmcnt(3)
	v_mfma_f32_32x32x16_bf16 v[98:113], v[154:157], v[118:121], 0
	s_waitcnt lgkmcnt(2)
	v_mfma_f32_32x32x16_bf16 v[98:113], v[162:165], v[122:125], v[98:113]
	s_waitcnt lgkmcnt(1)
	v_mfma_f32_32x32x16_bf16 v[98:113], v[190:193], v[126:129], v[98:113]
	s_waitcnt lgkmcnt(0)
	v_mfma_f32_32x32x16_bf16 v[98:113], v[206:209], v[134:137], v[98:113]
	s_cbranch_scc1 .LBB0_84
	v_add_u32_e32 v152, s4, v179
	v_cmp_le_i32_e32 vcc, v152, v183
	v_add_u32_e32 v154, 2, v152
	s_nop 7
	v_cndmask_b32_e32 v98, v220, v98, vcc
	v_cmp_lt_i32_e32 vcc, v152, v173
	s_nop 1
	v_cndmask_b32_e32 v83, v220, v83, vcc
	v_cmp_le_i32_e32 vcc, v152, v173
	s_nop 1
	v_cndmask_b32_e32 v82, v220, v82, vcc
	v_cmp_le_i32_e32 vcc, v152, v184
	s_nop 1
	v_cndmask_b32_e32 v99, v220, v99, vcc
	v_cmp_le_i32_e32 vcc, v154, v173
	v_add_u32_e32 v154, 3, v152
	s_nop 0
	v_cndmask_b32_e32 v84, v220, v84, vcc
	v_cmp_le_i32_e32 vcc, v152, v185
	s_nop 1
	v_cndmask_b32_e32 v100, v220, v100, vcc
	v_cmp_le_i32_e32 vcc, v154, v173
	s_nop 1
	v_cndmask_b32_e32 v85, v220, v85, vcc
	v_cmp_le_i32_e32 vcc, v152, v186
	s_nop 1
	v_cndmask_b32_e32 v101, v220, v101, vcc
	v_cmp_le_i32_e32 vcc, v152, v187
	s_nop 1
	v_cndmask_b32_e32 v86, v220, v86, vcc
	v_cmp_le_i32_e32 vcc, v152, v188
	s_nop 1
	v_cndmask_b32_e32 v102, v220, v102, vcc
	v_cmp_le_i32_e32 vcc, v152, v189
	s_nop 1
	v_cndmask_b32_e32 v87, v220, v87, vcc
	v_cmp_le_i32_e32 vcc, v152, v195
	s_nop 1
	v_cndmask_b32_e32 v103, v220, v103, vcc
	v_cmp_le_i32_e32 vcc, v152, v196
	s_nop 1
	v_cndmask_b32_e32 v88, v220, v88, vcc
	v_cmp_le_i32_e32 vcc, v152, v197
	s_nop 1
	v_cndmask_b32_e32 v104, v220, v104, vcc
	v_cmp_le_i32_e32 vcc, v152, v198
	s_nop 1
	v_cndmask_b32_e32 v89, v220, v89, vcc
	v_cmp_le_i32_e32 vcc, v152, v199
	s_nop 1
	v_cndmask_b32_e32 v105, v220, v105, vcc
	v_cmp_le_i32_e32 vcc, v152, v200
	s_nop 1
	v_cndmask_b32_e32 v90, v220, v90, vcc
	v_cmp_le_i32_e32 vcc, v152, v201
	s_nop 1
	v_cndmask_b32_e32 v106, v220, v106, vcc
	v_cmp_le_i32_e32 vcc, v152, v202
	s_nop 1
	v_cndmask_b32_e32 v91, v220, v91, vcc
	v_cmp_le_i32_e32 vcc, v152, v203
	s_nop 1
	v_cndmask_b32_e32 v107, v220, v107, vcc
	v_cmp_le_i32_e32 vcc, v152, v204
	s_nop 1
	v_cndmask_b32_e32 v92, v220, v92, vcc
	v_cmp_le_i32_e32 vcc, v152, v205
	s_nop 1
	v_cndmask_b32_e32 v108, v220, v108, vcc
	v_cmp_le_i32_e32 vcc, v152, v228
	s_nop 1
	v_cndmask_b32_e32 v93, v220, v93, vcc
	v_cmp_le_i32_e32 vcc, v152, v229
	s_nop 1
	v_cndmask_b32_e32 v109, v220, v109, vcc
	v_cmp_le_i32_e32 vcc, v152, v230
	s_nop 1
	v_cndmask_b32_e32 v94, v220, v94, vcc
	v_cmp_le_i32_e32 vcc, v152, v231
	s_nop 1
	v_cndmask_b32_e32 v110, v220, v110, vcc
	v_cmp_le_i32_e32 vcc, v152, v232
	s_nop 1
	v_cndmask_b32_e32 v95, v220, v95, vcc
	v_cmp_le_i32_e32 vcc, v152, v233
	s_nop 1
	v_cndmask_b32_e32 v111, v220, v111, vcc
	v_cmp_le_i32_e32 vcc, v152, v234
	s_nop 1
	v_cndmask_b32_e32 v96, v220, v96, vcc
	v_cmp_le_i32_e32 vcc, v152, v235
	s_nop 1
	v_cndmask_b32_e32 v112, v220, v112, vcc
	v_cmp_le_i32_e32 vcc, v152, v236
	s_nop 1
	v_cndmask_b32_e32 v97, v220, v97, vcc
	v_cmp_le_i32_e32 vcc, v152, v237
	s_nop 1
	v_cndmask_b32_e32 v113, v220, v113, vcc

.LBB0_90:
	v_add3_u32 v153, s26, v182, v181
	s_mov_b32 s78, s76
	s_mov_b32 s79, s76
	s_mov_b32 s77, s76
	ds_read_b64_tr_b16 v[154:155], v153 offset:9216
	ds_read_b64_tr_b16 v[156:157], v153 offset:11392
	ds_read_b64_tr_b16 v[162:163], v153 offset:9280
	ds_read_b64_tr_b16 v[164:165], v153 offset:11456
	ds_read_b64_tr_b16 v[190:191], v153 offset:9344
	ds_read_b64_tr_b16 v[192:193], v153 offset:11520
	ds_read_b64_tr_b16 v[206:207], v153 offset:9408
	ds_read_b64_tr_b16 v[208:209], v153 offset:11584
	v_sub_f32_e32 v82, v82, v152
	v_sub_f32_e32 v83, v83, v152
	v_sub_f32_e32 v84, v84, v152
	v_sub_f32_e32 v85, v85, v152
	v_sub_f32_e32 v86, v86, v152
	v_sub_f32_e32 v87, v87, v152
	v_sub_f32_e32 v88, v88, v152
	v_sub_f32_e32 v89, v89, v152
	v_exp_f32_e32 v82, v82
	v_exp_f32_e32 v83, v83
	v_exp_f32_e32 v84, v84
	v_exp_f32_e32 v85, v85
	v_exp_f32_e32 v86, v86
	v_exp_f32_e32 v87, v87
	v_exp_f32_e32 v88, v88
	v_exp_f32_e32 v89, v89
	v_cvt_pk_bf16_f32 v82, v82, v83
	v_cvt_pk_bf16_f32 v83, v84, v85
	v_cvt_pk_bf16_f32 v84, v86, v87
	v_cvt_pk_bf16_f32 v85, v88, v89
	v_mov_b64_e32 v[88:89], s[78:79]
	v_mov_b64_e32 v[86:87], s[76:77]
	s_waitcnt lgkmcnt(6)
	v_mfma_f32_32x32x16_bf16 v[2:17], v[82:85], v[154:157], v[2:17]
	v_sub_f32_e32 v90, v90, v152
	v_sub_f32_e32 v91, v91, v152
	v_sub_f32_e32 v92, v92, v152
	v_sub_f32_e32 v93, v93, v152
	ds_read_b64_tr_b16 v[154:155], v153 offset:13568
	ds_read_b64_tr_b16 v[156:157], v153 offset:15744
	s_waitcnt lgkmcnt(6)
	v_mfma_f32_32x32x16_bf16 v[50:65], v[82:85], v[162:165], v[50:65]
	v_sub_f32_e32 v94, v94, v152
	v_sub_f32_e32 v95, v95, v152
	v_sub_f32_e32 v96, v96, v152
	v_sub_f32_e32 v97, v97, v152
	ds_read_b64_tr_b16 v[162:163], v153 offset:13632
	ds_read_b64_tr_b16 v[164:165], v153 offset:15808
	s_waitcnt lgkmcnt(6)
	v_mfma_f32_32x32x16_bf16 v[18:33], v[82:85], v[190:193], v[18:33]
	v_exp_f32_e32 v90, v90
	v_exp_f32_e32 v91, v91
	v_exp_f32_e32 v92, v92
	v_exp_f32_e32 v93, v93
	ds_read_b64_tr_b16 v[190:191], v153 offset:13696
	ds_read_b64_tr_b16 v[192:193], v153 offset:15872
	s_waitcnt lgkmcnt(6)
	v_mfma_f32_32x32x16_bf16 v[34:49], v[82:85], v[206:209], v[34:49]
	v_exp_f32_e32 v94, v94
	v_exp_f32_e32 v95, v95
	v_exp_f32_e32 v96, v96
	v_exp_f32_e32 v97, v97
	ds_read_b64_tr_b16 v[206:207], v153 offset:13760
	ds_read_b64_tr_b16 v[208:209], v153 offset:15936
	v_mfma_f32_32x32x16_bf16 v[66:81], v[82:85], v[86:89], v[66:81]
	v_cvt_pk_bf16_f32 v90, v90, v91
	v_cvt_pk_bf16_f32 v91, v92, v93
	v_cvt_pk_bf16_f32 v92, v94, v95
	v_cvt_pk_bf16_f32 v93, v96, v97
	s_nop 0
	s_waitcnt lgkmcnt(6)
	v_mfma_f32_32x32x16_bf16 v[2:17], v[90:93], v[154:157], v[2:17]
	v_sub_f32_e32 v98, v98, v152
	v_sub_f32_e32 v99, v99, v152
	v_sub_f32_e32 v100, v100, v152
	v_sub_f32_e32 v101, v101, v152
	ds_read_b64_tr_b16 v[154:155], v153 offset:17920
	ds_read_b64_tr_b16 v[156:157], v153 offset:20096
	s_waitcnt lgkmcnt(6)
	v_mfma_f32_32x32x16_bf16 v[50:65], v[90:93], v[162:165], v[50:65]
	v_sub_f32_e32 v102, v102, v152
	v_sub_f32_e32 v103, v103, v152
	v_sub_f32_e32 v104, v104, v152
	v_sub_f32_e32 v105, v105, v152
	ds_read_b64_tr_b16 v[162:163], v153 offset:17984
	ds_read_b64_tr_b16 v[164:165], v153 offset:20160
	s_waitcnt lgkmcnt(6)
	v_mfma_f32_32x32x16_bf16 v[18:33], v[90:93], v[190:193], v[18:33]
	v_exp_f32_e32 v98, v98
	v_exp_f32_e32 v99, v99
	v_exp_f32_e32 v100, v100
	v_exp_f32_e32 v101, v101
	ds_read_b64_tr_b16 v[190:191], v153 offset:18048
	ds_read_b64_tr_b16 v[192:193], v153 offset:20224
	s_waitcnt lgkmcnt(6)
	v_mfma_f32_32x32x16_bf16 v[34:49], v[90:93], v[206:209], v[34:49]
	v_exp_f32_e32 v102, v102
	v_exp_f32_e32 v103, v103
	v_exp_f32_e32 v104, v104
	v_exp_f32_e32 v105, v105
	ds_read_b64_tr_b16 v[206:207], v153 offset:18112
	ds_read_b64_tr_b16 v[208:209], v153 offset:20288
	v_mfma_f32_32x32x16_bf16 v[66:81], v[90:93], v[86:89], v[66:81]
	v_cvt_pk_bf16_f32 v98, v98, v99
	v_cvt_pk_bf16_f32 v99, v100, v101
	v_cvt_pk_bf16_f32 v100, v102, v103
	v_cvt_pk_bf16_f32 v101, v104, v105
	s_nop 0
	s_waitcnt lgkmcnt(6)
	v_mfma_f32_32x32x16_bf16 v[2:17], v[98:101], v[154:157], v[2:17]
	v_sub_f32_e32 v106, v106, v152
	v_sub_f32_e32 v107, v107, v152
	v_sub_f32_e32 v108, v108, v152
	v_sub_f32_e32 v109, v109, v152
	ds_read_b64_tr_b16 v[154:155], v153 offset:22272
	ds_read_b64_tr_b16 v[156:157], v153 offset:24448
	s_waitcnt lgkmcnt(6)
	v_mfma_f32_32x32x16_bf16 v[50:65], v[98:101], v[162:165], v[50:65]
	v_sub_f32_e32 v110, v110, v152
	v_sub_f32_e32 v111, v111, v152
	v_sub_f32_e32 v112, v112, v152
	v_sub_f32_e32 v113, v113, v152
	ds_read_b64_tr_b16 v[162:163], v153 offset:22336
	ds_read_b64_tr_b16 v[164:165], v153 offset:24512
	s_waitcnt lgkmcnt(6)
	v_mfma_f32_32x32x16_bf16 v[18:33], v[98:101], v[190:193], v[18:33]
	v_exp_f32_e32 v106, v106
	v_exp_f32_e32 v107, v107
	v_exp_f32_e32 v108, v108
	v_exp_f32_e32 v109, v109
	ds_read_b64_tr_b16 v[190:191], v153 offset:22400
	ds_read_b64_tr_b16 v[192:193], v153 offset:24576
	s_waitcnt lgkmcnt(6)
	v_mfma_f32_32x32x16_bf16 v[34:49], v[98:101], v[206:209], v[34:49]
	v_exp_f32_e32 v110, v110
	v_exp_f32_e32 v111, v111
	v_exp_f32_e32 v112, v112
	v_exp_f32_e32 v113, v113
	ds_read_b64_tr_b16 v[206:207], v153 offset:22464
	ds_read_b64_tr_b16 v[208:209], v153 offset:24640
	v_mfma_f32_32x32x16_bf16 v[66:81], v[98:101], v[86:89], v[66:81]
	v_cvt_pk_bf16_f32 v106, v106, v107
	v_cvt_pk_bf16_f32 v107, v108, v109
	v_cvt_pk_bf16_f32 v108, v110, v111
	v_cvt_pk_bf16_f32 v109, v112, v113
	s_nop 0
	s_waitcnt lgkmcnt(6)
	v_mfma_f32_32x32x16_bf16 v[2:17], v[106:109], v[154:157], v[2:17]
	s_waitcnt lgkmcnt(4)
	v_mfma_f32_32x32x16_bf16 v[50:65], v[106:109], v[162:165], v[50:65]
	s_waitcnt lgkmcnt(2)
	v_mfma_f32_32x32x16_bf16 v[18:33], v[106:109], v[190:193], v[18:33]
	s_waitcnt lgkmcnt(0)
	v_mfma_f32_32x32x16_bf16 v[34:49], v[106:109], v[206:209], v[34:49]
	v_mfma_f32_32x32x16_bf16 v[66:81], v[106:109], v[86:89], v[66:81]
	s_movk_i32 s77, 0x110
	s_andn2_b64 vcc, exec, s[28:29]
	s_cbranch_vccnz .LBB0_92
